# mix_b QK-norm/rope row pass rewritten: lane = 16*head + j, 16B/8B loads and stores, DPP reductions over 16 lanes, rope partner via DPP
# speedup vs baseline: 1.1406x; 1.0226x over previous
; __device__ __forceinline__ void phase_mix_b(const Params& p, int l, bool last, unsigned char* smem) {
;     ...
;   const int tt = tid_(), lane = tt & 63, wid = tt >> 6;
;   const int gw = bid_() * 4 + wid, nw = gridDim.x * 4;
;   const float QSCALE = 0.07216878364870322f * 1.4426950408889634f;
;   for (int row = gw; row < TT; row += nw) {
;     const bool lat = row < T_LAT;
;     const int b = row_batch(row), pos = row_pos(row);
;     float cs = 1.f, sn = 0.f;
;     if (lat) {
;       const int n = row & (SEQ - 1);
;       const int r = lane, sub = r & 31, i = sub & 15;
;       const float ps = (r < 32) ? (float)(n >> 6) : (float)(n & 63);
;       const float fr = __builtin_amdgcn_exp2f(-(float)i * 0.83048202372184058696f);
;       const float ang = ps * fr;
;       sn = __sinf(ang);
;       cs = __cosf(ang);
;     }
;     const bool hi = ((lane & 31) >= 16);
;     if (lat || !last) {
; #pragma unroll
;       for (int h = 0; h < 4; ++h) {
;         const u16* q = p.QR + (size_t)row * 768 + h * 192;
;         float v0 = bf2f(q[lane]), v1 = bf2f(q[lane + 64]), v2 = bf2f(q[lane + 128]);
;         const float ss = wave_sum(v0 * v0 + v1 * v1 + v2 * v2);
;         const float rstd = rsqrtf(ss * (1.f / 192.f) + 1e-6f);
;         const float* qn = p.q_norm + l * 192;
;         v0 *= rstd * qn[lane]; v1 *= rstd * qn[lane + 64]; v2 *= rstd * qn[lane + 128];
;         if (lat) {
;           const float xp = __shfl_xor(v2, 16);
;           v2 = hi ? (xp * sn + v2 * cs) : (v2 * cs - xp * sn);
;         }
;         u16* o = p.Qall + ((size_t)(b * 4 + h) * NPOS + pos) * 192;
;         o[lane] = f2bf(v0 * QSCALE); o[lane + 64] = f2bf(v1 * QSCALE); o[lane + 128] = f2bf(v2 * QSCALE);
;       }
;     }
;     {
;       const float kr = bf2f(p.PX[(size_t)row * 1024 + 896 + lane]);
; #pragma unroll
;       for (int h = 0; h < 4; ++h) {
;         const u16* kk = p.KN + (size_t)row * 512 + h * 128;
;         float v0 = bf2f(kk[lane]), v1 = bf2f(kk[lane + 64]), v2 = kr;
;         const float ss = wave_sum(v0 * v0 + v1 * v1 + v2 * v2);
;         const float rstd = rsqrtf(ss * (1.f / 192.f) + 1e-6f);
;         const float* kn = p.k_norm + l * 192;
;         v0 *= rstd * kn[lane]; v1 *= rstd * kn[lane + 64]; v2 *= rstd * kn[lane + 128];
;         if (lat) {
;           const float xp = __shfl_xor(v2, 16);
;           v2 = hi ? (xp * sn + v2 * cs) : (v2 * cs - xp * sn);
;         }
.LBB0_686:
	s_waitcnt vmcnt(0)
	s_mov_b64 s[0:1], exec
	s_load_dwordx4 s[40:43], s[64:65], 0x70
	s_load_dwordx2 s[46:47], s[64:65], 0x120
	s_load_dwordx4 s[48:51], s[64:65], 0x148
	s_load_dwordx2 s[52:53], s[64:65], 0x160
	s_load_dwordx2 s[56:57], s[64:65], 0x168
	v_and_b32_e32 v2, 63, v187
	v_lshrrev_b32_e32 v3, 6, v187
	v_and_b32_e32 v4, 15, v2
	v_lshrrev_b32_e32 v5, 4, v2
	v_readfirstlane_b32 s8, v3
	v_readlane_b32 s9, v254, 47
	v_lshlrev_b32_e32 v6, 4, v4
	v_lshlrev_b32_e32 v7, 3, v4
	v_mul_u32_u24_e32 v8, 0x180, v5
	v_add_u32_e32 v150, v8, v6
	v_add_u32_e32 v151, v8, v7
	v_add_u32_e32 v151, 0x100, v151
	v_lshl_add_u32 v152, v5, 8, v6
	v_mov_b32_e32 v153, v7
	v_mul_u32_u24_e32 v9, 0x318000, v5
	v_add_u32_e32 v154, v9, v6
	v_add_u32_e32 v155, v9, v7
	v_add_u32_e32 v155, 0x100, v155
	v_and_b32_e32 v10, 3, v4
	v_lshlrev_b32_e32 v10, 2, v10
	v_bfe_u32 v11, v4, 3, 1
	v_bfe_u32 v12, v4, 2, 1
	v_cmp_eq_u32_e64 s[38:39], 0, v11
	v_add_u32_e32 v13, 0, v10
	v_cvt_f32_u32_e32 v13, v13
	v_mul_f32_e32 v13, 0xbf549a78, v13
	v_exp_f32_e32 v13, v13
	s_nop 0
	v_cndmask_b32_e64 v180, 0, v13, s[38:39]
	v_cndmask_b32_e64 v184, v13, 0, s[38:39]
	v_add_u32_e32 v13, 1, v10
	v_cvt_f32_u32_e32 v13, v13
	v_mul_f32_e32 v13, 0xbf549a78, v13
	v_exp_f32_e32 v13, v13
	s_nop 0
	v_cndmask_b32_e64 v181, 0, v13, s[38:39]
	v_cndmask_b32_e64 v185, v13, 0, s[38:39]
	v_add_u32_e32 v13, 2, v10
	v_cvt_f32_u32_e32 v13, v13
	v_mul_f32_e32 v13, 0xbf549a78, v13
	v_exp_f32_e32 v13, v13
	s_nop 0
	v_cndmask_b32_e64 v182, 0, v13, s[38:39]
	v_cndmask_b32_e64 v188, v13, 0, s[38:39]
	v_add_u32_e32 v13, 3, v10
	v_cvt_f32_u32_e32 v13, v13
	v_mul_f32_e32 v13, 0xbf549a78, v13
	v_exp_f32_e32 v13, v13
	s_nop 0
	v_cndmask_b32_e64 v183, 0, v13, s[38:39]
	v_cndmask_b32_e64 v189, v13, 0, s[38:39]
	v_cmp_eq_u32_e64 s[38:39], 0, v12
	v_mov_b32_e32 v13, 0x3e22f983
	s_nop 1
	v_cndmask_b32_e64 v190, v13, -v13, s[38:39]
	s_waitcnt lgkmcnt(0)
	s_nop 3
	s_mul_i32 s18, s36, 0x300
	s_add_u32 s40, s40, s18
	s_addc_u32 s41, s41, 0
	s_add_u32 s42, s42, s18
	s_addc_u32 s43, s43, 0
	v_lshlrev_b32_e32 v13, 5, v4
	global_load_dwordx4 v[156:159], v13, s[40:41]
	global_load_dwordx4 v[160:163], v13, s[40:41] offset:16
	global_load_dwordx4 v[164:167], v6, s[40:41] offset:512
	global_load_dwordx4 v[168:171], v13, s[42:43]
	global_load_dwordx4 v[172:175], v13, s[42:43] offset:16
	global_load_dwordx4 v[176:179], v6, s[42:43] offset:512
	s_lshl_b32 s94, s2, 2
	s_add_i32 s94, s94, s8
	s_cmp_lt_u32 s94, 0x4200
	s_cbranch_scc0 .Lmb_done
.Lmb_row:
	s_cmp_lt_u32 s94, 0x4000
	s_cbranch_scc0 .Lmb_ctxrow
	s_lshr_b32 s32, s94, 13
	s_and_b32 s35, s94, 0x1fff
	s_add_i32 s38, s35, 0x100
	s_lshr_b32 s39, s35, 6
	s_and_b32 s35, s35, 63
	s_mov_b32 s59, 1
	s_mov_b32 s60, 1
	s_branch .Lmb_rowgo
.Lmb_ctxrow:
	s_sub_i32 s35, s94, 0x4000
	s_lshr_b32 s32, s35, 8
	s_and_b32 s38, s35, 0xff
	s_mov_b32 s59, 0
	s_mov_b32 s60, 1
	s_cmp_eq_u64 s[86:87], 0
	s_cbranch_scc1 .Lmb_rowgo
	s_mov_b32 s60, 0
.Lmb_rowgo:
	s_lshl_b32 s32, s32, 2
	s_mul_i32 s32, s32, 0x2100
	s_add_i32 s32, s32, s38
	s_mul_i32 s32, s32, 0x180
	s_add_u32 s88, s52, s32
	s_addc_u32 s89, s53, 0
	s_add_u32 s100, s56, s32
	s_addc_u32 s101, s57, 0
	s_mul_i32 s32, s94, 0x600
	s_add_u32 s4, s48, s32
	s_addc_u32 s5, s49, 0
	s_lshl_b32 s32, s94, 10
	s_add_u32 s98, s50, s32
	s_addc_u32 s99, s51, 0
	s_lshl_b32 s32, s94, 11
	s_add_u32 s18, s46, s32
	s_addc_u32 s19, s47, 0
	global_load_dwordx4 v[8:11], v152, s[98:99]
	global_load_dwordx2 v[12:13], v153, s[18:19] offset:1792
	s_cmp_eq_u32 s60, 0
	s_cbranch_scc1 .Lmb_noqload
	global_load_dwordx4 v[2:5], v150, s[4:5]
	global_load_dwordx2 v[6:7], v151, s[4:5]
.Lmb_noqload:
	s_cmp_eq_u32 s59, 0
	s_cbranch_scc1 .Lmb_norope_a
	v_cvt_f32_u32_e32 v200, s39
	v_cvt_f32_u32_e32 v201, s35
	v_mul_f32_e32 v199, v200, v180
	v_fmac_f32_e32 v199, v201, v184
	v_mul_f32_e32 v199, v190, v199
	v_sin_f32_e32 v195, v199
	v_cos_f32_e32 v191, v199
	v_mul_f32_e32 v199, v200, v181
	v_fmac_f32_e32 v199, v201, v185
	v_mul_f32_e32 v199, v190, v199
	v_sin_f32_e32 v196, v199
	v_cos_f32_e32 v192, v199
	v_mul_f32_e32 v199, v200, v182
	v_fmac_f32_e32 v199, v201, v188
	v_mul_f32_e32 v199, v190, v199
	v_sin_f32_e32 v197, v199
	v_cos_f32_e32 v193, v199
	v_mul_f32_e32 v199, v200, v183
	v_fmac_f32_e32 v199, v201, v189
	v_mul_f32_e32 v199, v190, v199
	v_sin_f32_e32 v198, v199
	v_cos_f32_e32 v194, v199
.Lmb_norope_a:
	s_waitcnt vmcnt(0)
	v_lshlrev_b32_e32 v26, 16, v8
	v_and_b32_e32 v27, 0xffff0000, v8
	v_lshlrev_b32_e32 v28, 16, v9
	v_and_b32_e32 v29, 0xffff0000, v9
	v_lshlrev_b32_e32 v30, 16, v10
	v_and_b32_e32 v31, 0xffff0000, v10
	v_lshlrev_b32_e32 v32, 16, v11
	v_and_b32_e32 v33, 0xffff0000, v11
	v_lshlrev_b32_e32 v34, 16, v12
	v_and_b32_e32 v35, 0xffff0000, v12
	v_lshlrev_b32_e32 v36, 16, v13
	v_and_b32_e32 v37, 0xffff0000, v13
	v_mul_f32_e32 v39, v26, v26
	v_fmac_f32_e32 v39, v27, v27
	v_fmac_f32_e32 v39, v28, v28
	v_fmac_f32_e32 v39, v29, v29
	v_fmac_f32_e32 v39, v30, v30
	v_fmac_f32_e32 v39, v31, v31
	v_fmac_f32_e32 v39, v32, v32
	v_fmac_f32_e32 v39, v33, v33
	v_fmac_f32_e32 v39, v34, v34
	v_fmac_f32_e32 v39, v35, v35
	v_fmac_f32_e32 v39, v36, v36
	v_fmac_f32_e32 v39, v37, v37
	s_cmp_eq_u32 s60, 0
	s_cbranch_scc1 .Lmb_noq1
	v_lshlrev_b32_e32 v14, 16, v2
	v_and_b32_e32 v15, 0xffff0000, v2
	v_lshlrev_b32_e32 v16, 16, v3
	v_and_b32_e32 v17, 0xffff0000, v3
	v_lshlrev_b32_e32 v18, 16, v4
	v_and_b32_e32 v19, 0xffff0000, v4
	v_lshlrev_b32_e32 v20, 16, v5
	v_and_b32_e32 v21, 0xffff0000, v5
	v_lshlrev_b32_e32 v22, 16, v6
	v_and_b32_e32 v23, 0xffff0000, v6
	v_lshlrev_b32_e32 v24, 16, v7
	v_and_b32_e32 v25, 0xffff0000, v7
	v_mul_f32_e32 v38, v14, v14
	v_fmac_f32_e32 v38, v15, v15
	v_fmac_f32_e32 v38, v16, v16
	v_fmac_f32_e32 v38, v17, v17
	v_fmac_f32_e32 v38, v18, v18
	v_fmac_f32_e32 v38, v19, v19
	v_fmac_f32_e32 v38, v20, v20
	v_fmac_f32_e32 v38, v21, v21
	v_fmac_f32_e32 v38, v22, v22
	v_fmac_f32_e32 v38, v23, v23
	v_fmac_f32_e32 v38, v24, v24
	v_fmac_f32_e32 v38, v25, v25
; __device__ __forceinline__ u16 f2bf(float f) { return (u16)(pack2(f, 0.f) & 0xffffu); }
; __device__ __forceinline__ float bf2f(u16 b) { return __uint_as_float(((unsigned)b) << 16); }
; __device__ __forceinline__ void phase_mix_b(const Params& p, int l, bool last, unsigned char* smem) {
;     ...
;     if (lat || !last) {
; #pragma unroll
;       for (int h = 0; h < 4; ++h) {
;         const u16* q = p.QR + (size_t)row * 768 + h * 192;
;         float v0 = bf2f(q[lane]), v1 = bf2f(q[lane + 64]), v2 = bf2f(q[lane + 128]);
;         const float ss = wave_sum(v0 * v0 + v1 * v1 + v2 * v2);
;         const float rstd = rsqrtf(ss * (1.f / 192.f) + 1e-6f);
;         const float* qn = p.q_norm + l * 192;
;         v0 *= rstd * qn[lane]; v1 *= rstd * qn[lane + 64]; v2 *= rstd * qn[lane + 128];
;         if (lat) {
;           const float xp = __shfl_xor(v2, 16);
;           v2 = hi ? (xp * sn + v2 * cs) : (v2 * cs - xp * sn);
;         }
;         u16* o = p.Qall + ((size_t)(b * 4 + h) * NPOS + pos) * 192;
;         o[lane] = f2bf(v0 * QSCALE); o[lane + 64] = f2bf(v1 * QSCALE); o[lane + 128] = f2bf(v2 * QSCALE);
;       }
;     }
;     {
;       const float kr = bf2f(p.PX[(size_t)row * 1024 + 896 + lane]);
; #pragma unroll
;       for (int h = 0; h < 4; ++h) {
;         const u16* kk = p.KN + (size_t)row * 512 + h * 128;
;         float v0 = bf2f(kk[lane]), v1 = bf2f(kk[lane + 64]), v2 = kr;
;         const float ss = wave_sum(v0 * v0 + v1 * v1 + v2 * v2);
;         const float rstd = rsqrtf(ss * (1.f / 192.f) + 1e-6f);
;         const float* kn = p.k_norm + l * 192;
;         v0 *= rstd * kn[lane]; v1 *= rstd * kn[lane + 64]; v2 *= rstd * kn[lane + 128];
;         if (lat) {
;           const float xp = __shfl_xor(v2, 16);
;           v2 = hi ? (xp * sn + v2 * cs) : (v2 * cs - xp * sn);
;         }
;         u16* o = p.Kb + ((size_t)(b * 4 + h) * NPOS + pos) * 192;
;         o[lane] = f2bf(v0); o[lane + 64] = f2bf(v1); o[lane + 128] = f2bf(v2);
;       }
;     }
;   }
.Lmb_noq1:
	s_nop 1
	v_add_f32_dpp v39, v39, v39 quad_perm:[1,0,3,2] row_mask:0xf bank_mask:0xf
	v_add_f32_dpp v38, v38, v38 quad_perm:[1,0,3,2] row_mask:0xf bank_mask:0xf
	s_nop 1
	v_add_f32_dpp v39, v39, v39 quad_perm:[2,3,0,1] row_mask:0xf bank_mask:0xf
	v_add_f32_dpp v38, v38, v38 quad_perm:[2,3,0,1] row_mask:0xf bank_mask:0xf
	s_nop 1
	v_add_f32_dpp v39, v39, v39 row_half_mirror row_mask:0xf bank_mask:0xf
	v_add_f32_dpp v38, v38, v38 row_half_mirror row_mask:0xf bank_mask:0xf
	s_nop 1
	v_add_f32_dpp v39, v39, v39 row_mirror row_mask:0xf bank_mask:0xf
	v_add_f32_dpp v38, v38, v38 row_mirror row_mask:0xf bank_mask:0xf
	v_fmamk_f32 v39, v39, 0x3baaaaab, v224
	v_rsq_f32_e32 v39, v39
	v_fmamk_f32 v38, v38, 0x3baaaaab, v224
	v_rsq_f32_e32 v38, v38
	s_nop 0
	v_mul_f32_e32 v210, v168, v39
	v_mul_f32_e32 v26, v210, v26
	v_mul_f32_e32 v210, v169, v39
	v_mul_f32_e32 v27, v210, v27
	v_mul_f32_e32 v210, v170, v39
	v_mul_f32_e32 v28, v210, v28
	v_mul_f32_e32 v210, v171, v39
	v_mul_f32_e32 v29, v210, v29
	v_mul_f32_e32 v210, v172, v39
	v_mul_f32_e32 v30, v210, v30
	v_mul_f32_e32 v210, v173, v39
	v_mul_f32_e32 v31, v210, v31
	v_mul_f32_e32 v210, v174, v39
	v_mul_f32_e32 v32, v210, v32
	v_mul_f32_e32 v210, v175, v39
	v_mul_f32_e32 v33, v210, v33
	v_mul_f32_e32 v210, v176, v39
	v_mul_f32_e32 v34, v210, v34
	v_mul_f32_e32 v210, v177, v39
	v_mul_f32_e32 v35, v210, v35
	v_mul_f32_e32 v210, v178, v39
	v_mul_f32_e32 v36, v210, v36
	v_mul_f32_e32 v210, v179, v39
	v_mul_f32_e32 v37, v210, v37
	s_cmp_eq_u32 s59, 0
	s_cbranch_scc1 .Lmb_kplain
	v_mul_f32_e32 v206, v34, v191
	v_mul_f32_e32 v207, v35, v192
	v_mul_f32_e32 v208, v36, v193
	v_mul_f32_e32 v209, v37, v194
	v_fmac_f32_dpp v206, v34, v195 row_shl:4 row_mask:0xf bank_mask:0x5
	v_fmac_f32_dpp v206, v34, v195 row_shr:4 row_mask:0xf bank_mask:0xa
	v_fmac_f32_dpp v207, v35, v196 row_shl:4 row_mask:0xf bank_mask:0x5
	v_fmac_f32_dpp v207, v35, v196 row_shr:4 row_mask:0xf bank_mask:0xa
	v_fmac_f32_dpp v208, v36, v197 row_shl:4 row_mask:0xf bank_mask:0x5
	v_fmac_f32_dpp v208, v36, v197 row_shr:4 row_mask:0xf bank_mask:0xa
	v_fmac_f32_dpp v209, v37, v198 row_shl:4 row_mask:0xf bank_mask:0x5
	v_fmac_f32_dpp v209, v37, v198 row_shr:4 row_mask:0xf bank_mask:0xa
	s_branch .Lmb_kpack
.Lmb_kplain:
	v_mov_b32_e32 v206, v34
	v_mov_b32_e32 v207, v35
	v_mov_b32_e32 v208, v36
	v_mov_b32_e32 v209, v37
.Lmb_kpack:
	v_cvt_pk_bf16_f32 v230, v26, v27
	v_cvt_pk_bf16_f32 v231, v28, v29
	v_cvt_pk_bf16_f32 v232, v30, v31
	v_cvt_pk_bf16_f32 v233, v32, v33
	v_cvt_pk_bf16_f32 v234, v206, v207
	v_cvt_pk_bf16_f32 v235, v208, v209
	global_store_dwordx4 v154, v[230:233], s[100:101]
	global_store_dwordx2 v155, v[234:235], s[100:101]
	s_cmp_eq_u32 s60, 0
	s_cbranch_scc1 .Lmb_next
	v_mul_f32_e32 v210, v156, v38
	v_mul_f32_e32 v14, v210, v14
	v_mul_f32_e32 v210, v157, v38
	v_mul_f32_e32 v15, v210, v15
	v_mul_f32_e32 v210, v158, v38
	v_mul_f32_e32 v16, v210, v16
	v_mul_f32_e32 v210, v159, v38
	v_mul_f32_e32 v17, v210, v17
	v_mul_f32_e32 v210, v160, v38
	v_mul_f32_e32 v18, v210, v18
	v_mul_f32_e32 v210, v161, v38
	v_mul_f32_e32 v19, v210, v19
	v_mul_f32_e32 v210, v162, v38
	v_mul_f32_e32 v20, v210, v20
	v_mul_f32_e32 v210, v163, v38
	v_mul_f32_e32 v21, v210, v21
	v_mul_f32_e32 v210, v164, v38
	v_mul_f32_e32 v22, v210, v22
	v_mul_f32_e32 v210, v165, v38
	v_mul_f32_e32 v23, v210, v23
	v_mul_f32_e32 v210, v166, v38
	v_mul_f32_e32 v24, v210, v24
	v_mul_f32_e32 v210, v167, v38
	v_mul_f32_e32 v25, v210, v25
	s_cmp_eq_u32 s59, 0
	s_cbranch_scc1 .Lmb_qplain
	v_mul_f32_e32 v202, v22, v191
	v_mul_f32_e32 v203, v23, v192
	v_mul_f32_e32 v204, v24, v193
	v_mul_f32_e32 v205, v25, v194
	v_fmac_f32_dpp v202, v22, v195 row_shl:4 row_mask:0xf bank_mask:0x5
	v_fmac_f32_dpp v202, v22, v195 row_shr:4 row_mask:0xf bank_mask:0xa
	v_fmac_f32_dpp v203, v23, v196 row_shl:4 row_mask:0xf bank_mask:0x5
	v_fmac_f32_dpp v203, v23, v196 row_shr:4 row_mask:0xf bank_mask:0xa
	v_fmac_f32_dpp v204, v24, v197 row_shl:4 row_mask:0xf bank_mask:0x5
	v_fmac_f32_dpp v204, v24, v197 row_shr:4 row_mask:0xf bank_mask:0xa
	v_fmac_f32_dpp v205, v25, v198 row_shl:4 row_mask:0xf bank_mask:0x5
	v_fmac_f32_dpp v205, v25, v198 row_shr:4 row_mask:0xf bank_mask:0xa
	s_branch .Lmb_qpack
.Lmb_qplain:
	v_mov_b32_e32 v202, v22
	v_mov_b32_e32 v203, v23
	v_mov_b32_e32 v204, v24
	v_mov_b32_e32 v205, v25
.Lmb_qpack:
	v_mul_f32_e32 v14, 0x3dd53b94, v14
	v_mul_f32_e32 v15, 0x3dd53b94, v15
	v_mul_f32_e32 v16, 0x3dd53b94, v16
	v_mul_f32_e32 v17, 0x3dd53b94, v17
	v_mul_f32_e32 v18, 0x3dd53b94, v18
	v_mul_f32_e32 v19, 0x3dd53b94, v19
	v_mul_f32_e32 v20, 0x3dd53b94, v20
	v_mul_f32_e32 v21, 0x3dd53b94, v21
	v_mul_f32_e32 v202, 0x3dd53b94, v202
	v_mul_f32_e32 v203, 0x3dd53b94, v203
	v_mul_f32_e32 v204, 0x3dd53b94, v204
	v_mul_f32_e32 v205, 0x3dd53b94, v205
	v_cvt_pk_bf16_f32 v216, v14, v15
	v_cvt_pk_bf16_f32 v217, v16, v17
	v_cvt_pk_bf16_f32 v218, v18, v19
	v_cvt_pk_bf16_f32 v219, v20, v21
	v_cvt_pk_bf16_f32 v220, v202, v203
	v_cvt_pk_bf16_f32 v221, v204, v205
	global_store_dwordx4 v154, v[216:219], s[88:89]
	global_store_dwordx2 v155, v[220:221], s[88:89]
.Lmb_next:
	s_add_i32 s94, s94, s9
	s_cmp_lt_u32 s94, 0x4200
	s_cbranch_scc1 .Lmb_row
.Lmb_done:
	s_branch .LBB0_711
